# grid barrier: last cross-XCD arriver releases every XCD generation word directly (removes TOPGEN->XGEN hop) on top of v052
# speedup vs baseline: 1.0126x; 1.0008x over previous
; __device__ __forceinline__ unsigned xb_ld(unsigned* p)              { return __hip_atomic_load(p, __ATOMIC_RELAXED, __HIP_MEMORY_SCOPE_AGENT); }
; __device__ __forceinline__ unsigned xb_add(unsigned* p, unsigned v) { return __hip_atomic_fetch_add(p, v, __ATOMIC_RELAXED, __HIP_MEMORY_SCOPE_AGENT); }
; #define XB_SPIN(cond, bar) do { unsigned _sp = 0; while (cond) { __builtin_amdgcn_s_sleep(1); \
;     if ((++_sp & 255u) == 0u) { if (xb_ld(&(bar)[XB_TMO])) break; if (_sp > XB_SPIN_CAP) { atomicAdd(&(bar)[XB_TMO], 1u); break; } } } } while (0)
; __device__ __forceinline__ void xcd_barrier(const XcdBarrier& b, int tid_in) {
;     ...
;             __builtin_amdgcn_fence(__ATOMIC_RELEASE, "agent");
;             asm volatile("s_waitcnt vmcnt(0)" ::: "memory");
;             const unsigned og = xb_add(&bar[XB_TOP], 1u);
;             const unsigned tg = og / nx;
;             if (og + 1u == (tg + 1u) * nx) xb_add(&bar[XB_TOPGEN], 1u);
;             else XB_SPIN(xb_ld(&bar[XB_TOPGEN]) == tg, bar);
;             __builtin_amdgcn_fence(__ATOMIC_ACQUIRE, "agent");
;             xb_add(&bar[XB_XGEN(b.x)], 1u);
.LBB0_239:
	s_andn2_saveexec_b64 s[10:11], s[10:11]
	s_cbranch_execz .LBB0_259
	v_readfirstlane_b32 s100, v2
	s_mov_b64 s[10:11], exec
	buffer_wbl2 sc1
	s_waitcnt lgkmcnt(0)
	s_waitcnt vmcnt(0)
	v_mbcnt_lo_u32_b32 v2, s10, 0
	v_mbcnt_hi_u32_b32 v2, s11, v2
	v_cmp_eq_u32_e32 vcc, 0, v2
	s_and_saveexec_b64 s[12:13], vcc
	s_cbranch_execz .LBB0_242
	s_bcnt1_i32_b64 s2, s[10:11]
	v_mov_b32_e32 v3, s2
	global_atomic_add v3, v212, v3, s[6:7] offset:1024 sc0
.LBB0_242:
	s_or_b64 exec, exec, s[12:13]
	v_cvt_f32_u32_e32 v4, v0
	s_waitcnt vmcnt(0)
	buffer_inv sc1
	v_readfirstlane_b32 s2, v3
	s_add_u32 s10, s6, 0x13500
	s_addc_u32 s11, s7, 0
	v_rcp_iflag_f32_e32 v4, v4
	v_add_u32_e32 v2, s2, v2
	v_add_u32_e32 v5, 1, v2
	s_mov_b64 s[14:15], -1
	v_mul_f32_e32 v3, 0x4f7ffffe, v4
	v_cvt_u32_f32_e32 v3, v3
	v_sub_u32_e32 v4, 0, v0
	v_mul_lo_u32 v4, v4, v3
	v_mul_hi_u32 v4, v3, v4
	v_add_u32_e32 v3, v3, v4
	v_mul_hi_u32 v3, v2, v3
	v_mul_lo_u32 v4, v3, v0
	v_sub_u32_e32 v2, v2, v4
	v_add_u32_e32 v6, 1, v3
	v_cmp_ge_u32_e32 vcc, v2, v0
	v_sub_u32_e32 v4, v2, v0
	s_nop 0
	v_cndmask_b32_e32 v3, v3, v6, vcc
	v_cndmask_b32_e32 v2, v2, v4, vcc
	v_add_u32_e32 v4, 1, v3
	v_cmp_ge_u32_e32 vcc, v2, v0
	s_nop 1
	v_cndmask_b32_e32 v4, v3, v4, vcc
	v_mul_lo_u32 v2, v0, v4
	v_add_u32_e32 v0, v2, v0
	v_cmp_ne_u32_e32 vcc, v5, v0
	v_mov_b64_e32 v[2:3], s[10:11]
	s_cbranch_vccnz .Lxrel_skip_0
	s_sub_u32 s98, s10, 0x1100
	s_subb_u32 s99, s11, 0
	global_atomic_add v1, v213, s[98:99]
	global_atomic_add v1, v213, s[98:99] offset:256
	global_atomic_add v1, v213, s[98:99] offset:512
	global_atomic_add v1, v213, s[98:99] offset:768
	global_atomic_add v1, v213, s[98:99] offset:1024
	global_atomic_add v1, v213, s[98:99] offset:1280
	global_atomic_add v1, v213, s[98:99] offset:1536
	global_atomic_add v1, v213, s[98:99] offset:1792
	global_atomic_add v1, v213, s[98:99] offset:2048
	global_atomic_add v1, v213, s[98:99] offset:2304
	global_atomic_add v1, v213, s[98:99] offset:2560
	global_atomic_add v1, v213, s[98:99] offset:2816
	global_atomic_add v1, v213, s[98:99] offset:3072
	global_atomic_add v1, v213, s[98:99] offset:3328
	global_atomic_add v1, v213, s[98:99] offset:3584
	global_atomic_add v1, v213, s[98:99] offset:3840
.Lxrel_skip_0:
	s_and_saveexec_b64 s[12:13], vcc
	s_cbranch_execz .LBB0_254
	s_add_u32 s10, s8, 0x2400
	s_addc_u32 s11, s9, 0
	v_mov_b32_e32 v4, s100
	global_load_dword v0, v1, s[10:11] sc1
	s_mov_b64 s[18:19], 0
	s_waitcnt vmcnt(0)
	v_cmp_eq_u32_e32 vcc, v0, v4
	s_and_saveexec_b64 s[16:17], vcc
	s_cbranch_execz .LBB0_253
	s_add_u32 s14, s6, 0x10200
	s_addc_u32 s15, s7, 0
	s_mov_b32 s2, 1
	s_mov_b64 s[6:7], 0
	s_branch .LBB0_246

; __device__ __forceinline__ unsigned xb_add(unsigned* p, unsigned v) { return __hip_atomic_fetch_add(p, v, __ATOMIC_RELAXED, __HIP_MEMORY_SCOPE_AGENT); }
; __device__ __forceinline__ void xcd_barrier(const XcdBarrier& b, int tid_in) {
;     ...
;             __builtin_amdgcn_fence(__ATOMIC_ACQUIRE, "agent");
;             xb_add(&bar[XB_XGEN(b.x)], 1u);
;             asm volatile("s_waitcnt vmcnt(0)" ::: "memory");
.LBB0_256:
	s_or_b64 exec, exec, s[6:7]
	s_mov_b64 s[6:7], exec
	v_mbcnt_lo_u32_b32 v0, s6, 0
	v_mbcnt_hi_u32_b32 v0, s7, v0
	v_cmp_eq_u32_e32 vcc, 0, v0
	s_waitcnt vmcnt(0)
	s_and_saveexec_b64 s[10:11], vcc
	s_cbranch_execz .LBB0_258
	s_bcnt1_i32_b64 s2, s[6:7]
	v_mov_b32_e32 v0, s2
.LBB0_258:
	s_or_b64 exec, exec, s[10:11]
	s_waitcnt vmcnt(0)

; __device__ __forceinline__ unsigned xb_add(unsigned* p, unsigned v) { return __hip_atomic_fetch_add(p, v, __ATOMIC_RELAXED, __HIP_MEMORY_SCOPE_AGENT); }
; __device__ __forceinline__ void xcd_barrier(const XcdBarrier& b, int tid_in) {
;     ...
;             __builtin_amdgcn_fence(__ATOMIC_ACQUIRE, "agent");
;             xb_add(&bar[XB_XGEN(b.x)], 1u);
;             asm volatile("s_waitcnt vmcnt(0)" ::: "memory");
.LBB0_518:
	s_or_b64 exec, exec, s[6:7]
	s_mov_b64 s[6:7], exec
	v_mbcnt_lo_u32_b32 v0, s6, 0
	v_mbcnt_hi_u32_b32 v0, s7, v0
	v_cmp_eq_u32_e32 vcc, 0, v0
	s_waitcnt vmcnt(0)
	s_and_saveexec_b64 s[10:11], vcc
	s_cbranch_execz .LBB0_520
	s_bcnt1_i32_b64 s2, s[6:7]
	v_mov_b32_e32 v0, s2
.LBB0_520:
	s_or_b64 exec, exec, s[10:11]
	s_waitcnt vmcnt(0)

; __device__ __forceinline__ unsigned xb_add(unsigned* p, unsigned v) { return __hip_atomic_fetch_add(p, v, __ATOMIC_RELAXED, __HIP_MEMORY_SCOPE_AGENT); }
; __device__ __forceinline__ void xcd_barrier(const XcdBarrier& b, int tid_in) {
;     ...
;             __builtin_amdgcn_fence(__ATOMIC_ACQUIRE, "agent");
;             xb_add(&bar[XB_XGEN(b.x)], 1u);
;             asm volatile("s_waitcnt vmcnt(0)" ::: "memory");
.LBB0_594:
	s_or_b64 exec, exec, s[6:7]
	s_mov_b64 s[6:7], exec
	v_mbcnt_lo_u32_b32 v0, s6, 0
	v_mbcnt_hi_u32_b32 v0, s7, v0
	v_cmp_eq_u32_e32 vcc, 0, v0
	s_waitcnt vmcnt(0)
	s_and_saveexec_b64 s[10:11], vcc
	s_cbranch_execz .LBB0_596
	s_bcnt1_i32_b64 s2, s[6:7]
	v_mov_b32_e32 v0, s2
.LBB0_596:
	s_or_b64 exec, exec, s[10:11]
	s_waitcnt vmcnt(0)

; __device__ __forceinline__ unsigned xb_add(unsigned* p, unsigned v) { return __hip_atomic_fetch_add(p, v, __ATOMIC_RELAXED, __HIP_MEMORY_SCOPE_AGENT); }
; __device__ __forceinline__ void xcd_barrier(const XcdBarrier& b, int tid_in) {
;     ...
;             __builtin_amdgcn_fence(__ATOMIC_ACQUIRE, "agent");
;             xb_add(&bar[XB_XGEN(b.x)], 1u);
;             asm volatile("s_waitcnt vmcnt(0)" ::: "memory");
.LBB0_659:
	s_or_b64 exec, exec, s[6:7]
	s_mov_b64 s[6:7], exec
	v_mbcnt_lo_u32_b32 v0, s6, 0
	v_mbcnt_hi_u32_b32 v0, s7, v0
	v_cmp_eq_u32_e32 vcc, 0, v0
	s_waitcnt vmcnt(0)
	s_and_saveexec_b64 s[10:11], vcc
	s_cbranch_execz .LBB0_661
	s_bcnt1_i32_b64 s2, s[6:7]
	v_mov_b32_e32 v0, s2
.LBB0_661:
	s_or_b64 exec, exec, s[10:11]
	s_waitcnt vmcnt(0)

; __device__ __forceinline__ unsigned xb_add(unsigned* p, unsigned v) { return __hip_atomic_fetch_add(p, v, __ATOMIC_RELAXED, __HIP_MEMORY_SCOPE_AGENT); }
; __device__ __forceinline__ void xcd_barrier(const XcdBarrier& b, int tid_in) {
;     ...
;             __builtin_amdgcn_fence(__ATOMIC_ACQUIRE, "agent");
;             xb_add(&bar[XB_XGEN(b.x)], 1u);
;             asm volatile("s_waitcnt vmcnt(0)" ::: "memory");
.LBB0_735:
	s_or_b64 exec, exec, s[6:7]
	s_mov_b64 s[6:7], exec
	v_mbcnt_lo_u32_b32 v0, s6, 0
	v_mbcnt_hi_u32_b32 v0, s7, v0
	v_cmp_eq_u32_e32 vcc, 0, v0
	s_waitcnt vmcnt(0)
	s_and_saveexec_b64 s[10:11], vcc
	s_cbranch_execz .LBB0_737
	s_bcnt1_i32_b64 s2, s[6:7]
	v_mov_b32_e32 v0, s2
.LBB0_737:
	s_or_b64 exec, exec, s[10:11]
	s_waitcnt vmcnt(0)

; __device__ __forceinline__ unsigned xb_add(unsigned* p, unsigned v) { return __hip_atomic_fetch_add(p, v, __ATOMIC_RELAXED, __HIP_MEMORY_SCOPE_AGENT); }
; __device__ __forceinline__ void xcd_barrier(const XcdBarrier& b, int tid_in) {
;     ...
;             __builtin_amdgcn_fence(__ATOMIC_ACQUIRE, "agent");
;             xb_add(&bar[XB_XGEN(b.x)], 1u);
;             asm volatile("s_waitcnt vmcnt(0)" ::: "memory");
.LBB0_811:
	s_or_b64 exec, exec, s[6:7]
	s_mov_b64 s[6:7], exec
	v_mbcnt_lo_u32_b32 v0, s6, 0
	v_mbcnt_hi_u32_b32 v0, s7, v0
	v_cmp_eq_u32_e32 vcc, 0, v0
	s_waitcnt vmcnt(0)
	s_and_saveexec_b64 s[10:11], vcc
	s_cbranch_execz .LBB0_813
	s_bcnt1_i32_b64 s2, s[6:7]
	v_mov_b32_e32 v0, s2
.LBB0_813:
	s_or_b64 exec, exec, s[10:11]
	s_waitcnt vmcnt(0)

; __device__ __forceinline__ unsigned xb_add(unsigned* p, unsigned v) { return __hip_atomic_fetch_add(p, v, __ATOMIC_RELAXED, __HIP_MEMORY_SCOPE_AGENT); }
; __device__ __forceinline__ void xcd_barrier(const XcdBarrier& b, int tid_in) {
;     ...
;             __builtin_amdgcn_fence(__ATOMIC_ACQUIRE, "agent");
;             xb_add(&bar[XB_XGEN(b.x)], 1u);
;             asm volatile("s_waitcnt vmcnt(0)" ::: "memory");
.LBB0_876:
	s_or_b64 exec, exec, s[6:7]
	s_mov_b64 s[6:7], exec
	v_mbcnt_lo_u32_b32 v0, s6, 0
	v_mbcnt_hi_u32_b32 v0, s7, v0
	v_cmp_eq_u32_e32 vcc, 0, v0
	s_waitcnt vmcnt(0)
	s_and_saveexec_b64 s[10:11], vcc
	s_cbranch_execz .LBB0_878
	s_bcnt1_i32_b64 s2, s[6:7]
	v_mov_b32_e32 v0, s2
.LBB0_878:
	s_or_b64 exec, exec, s[10:11]
	s_waitcnt vmcnt(0)

; __device__ __forceinline__ unsigned xb_add(unsigned* p, unsigned v) { return __hip_atomic_fetch_add(p, v, __ATOMIC_RELAXED, __HIP_MEMORY_SCOPE_AGENT); }
; __device__ __forceinline__ void xcd_barrier(const XcdBarrier& b, int tid_in) {
;     ...
;             __builtin_amdgcn_fence(__ATOMIC_ACQUIRE, "agent");
;             xb_add(&bar[XB_XGEN(b.x)], 1u);
;             asm volatile("s_waitcnt vmcnt(0)" ::: "memory");
.LBB0_976:
	s_or_b64 exec, exec, s[6:7]
	s_mov_b64 s[6:7], exec
	v_mbcnt_lo_u32_b32 v0, s6, 0
	v_mbcnt_hi_u32_b32 v0, s7, v0
	v_cmp_eq_u32_e32 vcc, 0, v0
	s_waitcnt vmcnt(0)
	s_and_saveexec_b64 s[10:11], vcc
	s_cbranch_execz .LBB0_978
	s_bcnt1_i32_b64 s2, s[6:7]
	v_mov_b32_e32 v0, s2
.LBB0_978:
	s_or_b64 exec, exec, s[10:11]
	s_waitcnt vmcnt(0)

; __device__ __forceinline__ unsigned xb_ld(unsigned* p)              { return __hip_atomic_load(p, __ATOMIC_RELAXED, __HIP_MEMORY_SCOPE_AGENT); }
; __device__ __forceinline__ unsigned xb_add(unsigned* p, unsigned v) { return __hip_atomic_fetch_add(p, v, __ATOMIC_RELAXED, __HIP_MEMORY_SCOPE_AGENT); }
; #define XB_SPIN(cond, bar) do { unsigned _sp = 0; while (cond) { __builtin_amdgcn_s_sleep(1); \
;     if ((++_sp & 255u) == 0u) { if (xb_ld(&(bar)[XB_TMO])) break; if (_sp > XB_SPIN_CAP) { atomicAdd(&(bar)[XB_TMO], 1u); break; } } } } while (0)
; __device__ __forceinline__ void xcd_barrier(const XcdBarrier& b, int tid_in) {
;     ...
;             __builtin_amdgcn_fence(__ATOMIC_RELEASE, "agent");
;             asm volatile("s_waitcnt vmcnt(0)" ::: "memory");
;             const unsigned og = xb_add(&bar[XB_TOP], 1u);
;             const unsigned tg = og / nx;
;             if (og + 1u == (tg + 1u) * nx) xb_add(&bar[XB_TOPGEN], 1u);
;             else XB_SPIN(xb_ld(&bar[XB_TOPGEN]) == tg, bar);
;             __builtin_amdgcn_fence(__ATOMIC_ACQUIRE, "agent");
;             xb_add(&bar[XB_XGEN(b.x)], 1u);
.LBB0_1038:
	s_andn2_saveexec_b64 s[10:11], s[10:11]
	s_cbranch_execz .LBB0_165
	v_readfirstlane_b32 s100, v2
	s_mov_b64 s[10:11], exec
	buffer_wbl2 sc1
	s_waitcnt lgkmcnt(0)
	s_waitcnt vmcnt(0)
	v_mbcnt_lo_u32_b32 v2, s10, 0
	v_mbcnt_hi_u32_b32 v2, s11, v2
	v_cmp_eq_u32_e32 vcc, 0, v2
	s_and_saveexec_b64 s[12:13], vcc
	s_cbranch_execz .LBB0_1041
	s_bcnt1_i32_b64 s10, s[10:11]
	v_mov_b32_e32 v3, s10
	global_atomic_add v3, v212, v3, s[6:7] offset:1024 sc0
.LBB0_1041:
	s_or_b64 exec, exec, s[12:13]
	v_cvt_f32_u32_e32 v4, v0
	s_waitcnt vmcnt(0)
	buffer_inv sc1
	v_readfirstlane_b32 s10, v3
	s_mov_b64 s[14:15], -1
	v_rcp_iflag_f32_e32 v4, v4
	v_add_u32_e32 v2, s10, v2
	v_add_u32_e32 v5, 1, v2
	s_add_u32 s10, s6, 0x13500
	v_mul_f32_e32 v3, 0x4f7ffffe, v4
	v_cvt_u32_f32_e32 v3, v3
	v_sub_u32_e32 v4, 0, v0
	s_addc_u32 s11, s7, 0
	v_mul_lo_u32 v4, v4, v3
	v_mul_hi_u32 v4, v3, v4
	v_add_u32_e32 v3, v3, v4
	v_mul_hi_u32 v3, v2, v3
	v_mul_lo_u32 v4, v3, v0
	v_sub_u32_e32 v2, v2, v4
	v_add_u32_e32 v6, 1, v3
	v_cmp_ge_u32_e32 vcc, v2, v0
	v_sub_u32_e32 v4, v2, v0
	s_nop 0
	v_cndmask_b32_e32 v3, v3, v6, vcc
	v_cndmask_b32_e32 v2, v2, v4, vcc
	v_add_u32_e32 v4, 1, v3
	v_cmp_ge_u32_e32 vcc, v2, v0
	s_nop 1
	v_cndmask_b32_e32 v4, v3, v4, vcc
	v_mul_lo_u32 v2, v0, v4
	v_add_u32_e32 v0, v2, v0
	v_cmp_ne_u32_e32 vcc, v5, v0
	v_mov_b64_e32 v[2:3], s[10:11]
	s_cbranch_vccnz .Lxrel_skip_8
	s_sub_u32 s98, s10, 0x1100
	s_subb_u32 s99, s11, 0
	global_atomic_add v1, v213, s[98:99]
	global_atomic_add v1, v213, s[98:99] offset:256
	global_atomic_add v1, v213, s[98:99] offset:512
	global_atomic_add v1, v213, s[98:99] offset:768
	global_atomic_add v1, v213, s[98:99] offset:1024
	global_atomic_add v1, v213, s[98:99] offset:1280
	global_atomic_add v1, v213, s[98:99] offset:1536
	global_atomic_add v1, v213, s[98:99] offset:1792
	global_atomic_add v1, v213, s[98:99] offset:2048
	global_atomic_add v1, v213, s[98:99] offset:2304
	global_atomic_add v1, v213, s[98:99] offset:2560
	global_atomic_add v1, v213, s[98:99] offset:2816
	global_atomic_add v1, v213, s[98:99] offset:3072
	global_atomic_add v1, v213, s[98:99] offset:3328
	global_atomic_add v1, v213, s[98:99] offset:3584
	global_atomic_add v1, v213, s[98:99] offset:3840
.Lxrel_skip_8:
	s_and_saveexec_b64 s[12:13], vcc
	s_cbranch_execz .LBB0_1053
	s_add_u32 s10, s8, 0x2400
	s_addc_u32 s11, s9, 0
	v_mov_b32_e32 v4, s100
	global_load_dword v0, v1, s[10:11] sc1
	s_mov_b64 s[18:19], 0
	s_waitcnt vmcnt(0)
	v_cmp_eq_u32_e32 vcc, v0, v4
	s_and_saveexec_b64 s[16:17], vcc
	s_cbranch_execz .LBB0_1052
	s_add_u32 s14, s6, 0x10200
	s_addc_u32 s15, s7, 0
	s_mov_b32 s26, 1
	s_mov_b64 s[6:7], 0
	s_branch .LBB0_1045

; __device__ __forceinline__ unsigned xb_add(unsigned* p, unsigned v) { return __hip_atomic_fetch_add(p, v, __ATOMIC_RELAXED, __HIP_MEMORY_SCOPE_AGENT); }
; __device__ __forceinline__ void xcd_barrier(const XcdBarrier& b, int tid_in) {
;     ...
;             __builtin_amdgcn_fence(__ATOMIC_ACQUIRE, "agent");
;             xb_add(&bar[XB_XGEN(b.x)], 1u);
;             asm volatile("s_waitcnt vmcnt(0)" ::: "memory");
.LBB0_1055:
	s_or_b64 exec, exec, s[6:7]
	s_mov_b64 s[6:7], exec
	v_mbcnt_lo_u32_b32 v0, s6, 0
	v_mbcnt_hi_u32_b32 v0, s7, v0
	v_cmp_eq_u32_e32 vcc, 0, v0
	s_waitcnt vmcnt(0)
	s_and_saveexec_b64 s[10:11], vcc
	s_cbranch_execz .LBB0_164
	s_bcnt1_i32_b64 s6, s[6:7]
	v_mov_b32_e32 v0, s6
	s_branch .LBB0_164
